# baseline (speedup 1.0000x reference)
;     ...
; #pragma unroll
;     for (int ai = 0; ai < 2; ++ai)
; #pragma unroll
;       for (int m = 0; m < 4; ++m) {
;         const int row = brow + ai * HALF + wr * 64 + m * 16 + fr;
;         float ssq = 0.f;
; #pragma unroll
;         for (int bj = 0; bj < 2; ++bj)
; #pragma unroll
;           for (int n = 0; n < 2; ++n) {
;             const int col = bcol + bj * HALF + wc * 32 + n * 16 + fq * 4;
;             f32x4 v = acc[ai][bj][m][n];
;             v += *(const f32x4*)(res + (long)row * D + col);
;             if (EPI == 7) *(f32x4*)(outf + (long)row * D + col) = v;
;             acc[ai][bj][m][n] = v;
;             ssq += v[0] * v[0] + v[1] * v[1] + v[2] * v[2] + v[3] * v[3];
;           }
;         ssq += bperm(ssq, lane ^ 16);
;         ssq += bperm(ssq, lane ^ 32);
;         if (fq == 0) p->sspart[(long)row * 64 + pn_ * 4 + wc] = ssq;
;         __builtin_amdgcn_sched_barrier(0);
.LBB0_1145:
	s_or_b64 exec, exec, s[28:29]
	s_nop 0
	v_or_b32_e32 v12, s24, v142
	v_lshrrev_b32_e32 v13, 2, v140
	v_add_u32_e32 v142, v143, v12
	v_lshlrev_b32_e32 v12, 5, v141
	v_and_b32_e32 v13, 12, v13
	v_or3_b32 v138, v12, v13, s26
	v_ashrrev_i32_e32 v143, 31, v142
	v_lshlrev_b64 v[146:147], 14, v[142:143]
	v_ashrrev_i32_e32 v139, 31, v138
	v_lshl_add_u64 v[12:13], s[10:11], 0, v[146:147]
	v_lshlrev_b64 v[144:145], 2, v[138:139]
	v_lshl_add_u64 v[24:25], v[12:13], 0, v[144:145]
	v_lshlrev_b32_e32 v254, 14, v142
	v_lshl_add_u32 v254, v138, 2, v254
	s_mov_b64 s[30:31], s[10:11]
	global_load_dwordx4 v[204:207], v254, s[30:31]
	global_load_dwordx4 v[208:211], v254, s[30:31] offset:64
	global_load_dwordx4 v[212:215], v254, s[30:31] offset:512
	global_load_dwordx4 v[216:219], v254, s[30:31] offset:576
	s_add_u32 s30, s10, 0x40000
	s_addc_u32 s31, s11, 0
	global_load_dwordx4 v[220:223], v254, s[30:31]
	global_load_dwordx4 v[224:227], v254, s[30:31] offset:64
	global_load_dwordx4 v[228:231], v254, s[30:31] offset:512
	global_load_dwordx4 v[232:235], v254, s[30:31] offset:576
	s_add_u32 s30, s10, 0x80000
	s_addc_u32 s31, s11, 0
	global_load_dwordx4 v[236:239], v254, s[30:31]
	global_load_dwordx4 v[240:243], v254, s[30:31] offset:64
	global_load_dwordx4 v[244:247], v254, s[30:31] offset:512
	global_load_dwordx4 v[248:251], v254, s[30:31] offset:576
	v_and_b32_e32 v24, 63, v140
	v_lshlrev_b32_e32 v25, 2, v24
	v_cmp_gt_u32_e32 vcc, 16, v24
	v_xor_b32_e32 v153, 64, v25
	v_xor_b32_e32 v152, 0x80, v25
	s_ashr_i32 s25, s45, 1
	s_and_b32 s26, s25, -4
	s_ashr_i32 s27, s26, 31
	v_lshlrev_b32_e32 v136, 2, v141
	s_waitcnt vmcnt(8)
	v_pk_add_f32 v[24:25], v[0:1], v[204:205]
	v_pk_add_f32 v[12:13], v[4:5], v[208:209]
	v_pk_add_f32 v[4:5], v[40:41], v[212:213]
	v_pk_add_f32 v[0:1], v[32:33], v[216:217]
	v_mul_f32_e32 v32, v25, v25
	v_mul_f32_e32 v33, v13, v13
	v_pk_add_f32 v[26:27], v[2:3], v[206:207]
	v_pk_add_f32 v[14:15], v[6:7], v[210:211]
	v_pk_add_f32 v[2:3], v[34:35], v[218:219]
	v_mul_f32_e32 v34, v5, v5
	v_fmac_f32_e32 v32, v24, v24
	v_fmac_f32_e32 v33, v12, v12
	v_pk_add_f32 v[6:7], v[42:43], v[214:215]
	v_mul_f32_e32 v35, v1, v1
	v_fmac_f32_e32 v34, v4, v4
	v_fmac_f32_e32 v32, v26, v26
	v_fmac_f32_e32 v33, v14, v14
	v_fmac_f32_e32 v35, v0, v0
	v_fmac_f32_e32 v34, v6, v6
	v_fmac_f32_e32 v32, v27, v27
	v_fmac_f32_e32 v33, v15, v15
	v_fmac_f32_e32 v35, v2, v2
	v_fmac_f32_e32 v34, v7, v7
	v_add_f32_e32 v32, v32, v33
	v_add_f32_e32 v32, v32, v34
	v_fmac_f32_e32 v35, v3, v3
	v_add_f32_e32 v40, v32, v35
	ds_bpermute_b32 v41, v153, v40
	v_lshl_add_u64 v[32:33], s[6:7], 0, v[146:147]
	v_lshl_add_u64 v[34:35], v[32:33], 0, v[144:145]
	global_store_dwordx4 v[34:35], v[24:27], off
	global_store_dwordx4 v[34:35], v[12:15], off offset:64
	global_store_dwordx4 v[34:35], v[4:7], off offset:512
	global_store_dwordx4 v[34:35], v[0:3], off offset:576
	s_waitcnt lgkmcnt(0)
	v_add_f32_e32 v32, v40, v41
	ds_bpermute_b32 v33, v152, v32
	s_and_saveexec_b64 s[28:29], vcc
	s_cbranch_execz .LBB0_1147
	s_load_dwordx2 s[30:31], s[2:3], 0x120
	s_waitcnt lgkmcnt(0)
	v_add_f32_e32 v34, v32, v33
	v_lshlrev_b64 v[32:33], 8, v[142:143]
	v_lshl_add_u64 v[32:33], s[30:31], 0, v[32:33]
	v_lshl_add_u64 v[32:33], s[26:27], 2, v[32:33]
	v_lshl_add_u64 v[32:33], v[32:33], 0, v[136:137]
	global_store_dword v[32:33], v34, off
.LBB0_1147:
	s_or_b64 exec, exec, s[28:29]
	v_or_b32_e32 v140, 16, v142
	v_ashrrev_i32_e32 v141, 31, v140
	v_lshlrev_b64 v[146:147], 14, v[140:141]
	s_waitcnt lgkmcnt(0)
	v_lshl_add_u64 v[32:33], s[10:11], 0, v[146:147]
	v_lshl_add_u64 v[40:41], v[32:33], 0, v[144:145]
	s_add_u32 s30, s10, 0xc0000
	s_addc_u32 s31, s11, 0
	global_load_dwordx4 v[204:207], v254, s[30:31]
	global_load_dwordx4 v[208:211], v254, s[30:31] offset:64
	global_load_dwordx4 v[212:215], v254, s[30:31] offset:512
	global_load_dwordx4 v[216:219], v254, s[30:31] offset:576
	s_waitcnt vmcnt(12)
	v_pk_add_f32 v[40:41], v[8:9], v[220:221]
	v_pk_add_f32 v[32:33], v[16:17], v[224:225]
	v_pk_add_f32 v[16:17], v[56:57], v[228:229]
	v_pk_add_f32 v[8:9], v[48:49], v[232:233]
	v_mul_f32_e32 v48, v41, v41
	v_mul_f32_e32 v49, v33, v33
	v_pk_add_f32 v[42:43], v[10:11], v[222:223]
	v_pk_add_f32 v[34:35], v[18:19], v[226:227]
	v_pk_add_f32 v[10:11], v[50:51], v[234:235]
	v_mul_f32_e32 v50, v17, v17
	v_fmac_f32_e32 v48, v40, v40
	v_fmac_f32_e32 v49, v32, v32
	v_pk_add_f32 v[18:19], v[58:59], v[230:231]
	v_mul_f32_e32 v51, v9, v9
	v_fmac_f32_e32 v50, v16, v16
	v_fmac_f32_e32 v48, v42, v42
	v_fmac_f32_e32 v49, v34, v34
	v_fmac_f32_e32 v51, v8, v8
	v_fmac_f32_e32 v50, v18, v18
	v_fmac_f32_e32 v48, v43, v43
	v_fmac_f32_e32 v49, v35, v35
	v_fmac_f32_e32 v51, v10, v10
	v_fmac_f32_e32 v50, v19, v19
	v_add_f32_e32 v48, v48, v49
	v_add_f32_e32 v48, v48, v50
	v_fmac_f32_e32 v51, v11, v11
	v_add_f32_e32 v56, v48, v51
	ds_bpermute_b32 v57, v153, v56
	v_lshl_add_u64 v[48:49], s[6:7], 0, v[146:147]
	v_lshl_add_u64 v[50:51], v[48:49], 0, v[144:145]
	global_store_dwordx4 v[50:51], v[40:43], off
	global_store_dwordx4 v[50:51], v[32:35], off offset:64
	global_store_dwordx4 v[50:51], v[16:19], off offset:512
	global_store_dwordx4 v[50:51], v[8:11], off offset:576
	s_waitcnt lgkmcnt(0)
	v_add_f32_e32 v48, v56, v57
	ds_bpermute_b32 v49, v152, v48
	s_and_saveexec_b64 s[28:29], vcc
	s_cbranch_execz .LBB0_1149
	s_load_dwordx2 s[30:31], s[2:3], 0x120
	s_waitcnt lgkmcnt(0)
	v_add_f32_e32 v50, v48, v49
	v_lshlrev_b64 v[48:49], 8, v[140:141]
	v_lshl_add_u64 v[48:49], s[30:31], 0, v[48:49]
	v_lshl_add_u64 v[48:49], s[26:27], 2, v[48:49]
	v_lshl_add_u64 v[48:49], v[48:49], 0, v[136:137]
	global_store_dword v[48:49], v50, off
;     ...
; #pragma unroll
;     for (int ai = 0; ai < 2; ++ai)
; #pragma unroll
;       for (int m = 0; m < 4; ++m) {
;         const int row = brow + ai * HALF + wr * 64 + m * 16 + fr;
;         float ssq = 0.f;
; #pragma unroll
;         for (int bj = 0; bj < 2; ++bj)
; #pragma unroll
;           for (int n = 0; n < 2; ++n) {
;             const int col = bcol + bj * HALF + wc * 32 + n * 16 + fq * 4;
;             f32x4 v = acc[ai][bj][m][n];
;             v += *(const f32x4*)(res + (long)row * D + col);
;             if (EPI == 7) *(f32x4*)(outf + (long)row * D + col) = v;
;             acc[ai][bj][m][n] = v;
;             ssq += v[0] * v[0] + v[1] * v[1] + v[2] * v[2] + v[3] * v[3];
;           }
;         ssq += bperm(ssq, lane ^ 16);
;         ssq += bperm(ssq, lane ^ 32);
;         if (fq == 0) p->sspart[(long)row * 64 + pn_ * 4 + wc] = ssq;
;         __builtin_amdgcn_sched_barrier(0);
.LBB0_1149:
	s_or_b64 exec, exec, s[28:29]
	v_or_b32_e32 v140, 32, v142
	v_ashrrev_i32_e32 v141, 31, v140
	v_lshlrev_b64 v[146:147], 14, v[140:141]
	s_waitcnt lgkmcnt(0)
	v_lshl_add_u64 v[48:49], s[10:11], 0, v[146:147]
	v_lshl_add_u64 v[56:57], v[48:49], 0, v[144:145]
	s_add_u32 s30, s10, 0x200000
	s_addc_u32 s31, s11, 0
	global_load_dwordx4 v[220:223], v254, s[30:31]
	global_load_dwordx4 v[224:227], v254, s[30:31] offset:64
	global_load_dwordx4 v[228:231], v254, s[30:31] offset:512
	global_load_dwordx4 v[232:235], v254, s[30:31] offset:576
	s_waitcnt vmcnt(16)
	v_pk_add_f32 v[56:57], v[20:21], v[236:237]
	v_pk_add_f32 v[48:49], v[28:29], v[240:241]
	v_pk_add_f32 v[28:29], v[72:73], v[244:245]
	v_pk_add_f32 v[20:21], v[64:65], v[248:249]
	v_mul_f32_e32 v64, v57, v57
	v_mul_f32_e32 v65, v49, v49
	v_pk_add_f32 v[58:59], v[22:23], v[238:239]
	v_pk_add_f32 v[50:51], v[30:31], v[242:243]
	v_pk_add_f32 v[22:23], v[66:67], v[250:251]
	v_mul_f32_e32 v66, v29, v29
	v_fmac_f32_e32 v64, v56, v56
	v_fmac_f32_e32 v65, v48, v48
	v_pk_add_f32 v[30:31], v[74:75], v[246:247]
	v_mul_f32_e32 v67, v21, v21
	v_fmac_f32_e32 v66, v28, v28
	v_fmac_f32_e32 v64, v58, v58
	v_fmac_f32_e32 v65, v50, v50
	v_fmac_f32_e32 v67, v20, v20
	v_fmac_f32_e32 v66, v30, v30
	v_fmac_f32_e32 v64, v59, v59
	v_fmac_f32_e32 v65, v51, v51
	v_fmac_f32_e32 v67, v22, v22
	v_fmac_f32_e32 v66, v31, v31
	v_add_f32_e32 v64, v64, v65
	v_add_f32_e32 v64, v64, v66
	v_fmac_f32_e32 v67, v23, v23
	v_add_f32_e32 v72, v64, v67
	ds_bpermute_b32 v73, v153, v72
	v_lshl_add_u64 v[64:65], s[6:7], 0, v[146:147]
	v_lshl_add_u64 v[66:67], v[64:65], 0, v[144:145]
	global_store_dwordx4 v[66:67], v[56:59], off
	global_store_dwordx4 v[66:67], v[48:51], off offset:64
	global_store_dwordx4 v[66:67], v[28:31], off offset:512
	global_store_dwordx4 v[66:67], v[20:23], off offset:576
	s_waitcnt lgkmcnt(0)
	v_add_f32_e32 v64, v72, v73
	ds_bpermute_b32 v65, v152, v64
	s_and_saveexec_b64 s[28:29], vcc
	s_cbranch_execz .LBB0_1151
	s_load_dwordx2 s[30:31], s[2:3], 0x120
	s_waitcnt lgkmcnt(0)
	v_add_f32_e32 v66, v64, v65
	v_lshlrev_b64 v[64:65], 8, v[140:141]
	v_lshl_add_u64 v[64:65], s[30:31], 0, v[64:65]
	v_lshl_add_u64 v[64:65], s[26:27], 2, v[64:65]
	v_lshl_add_u64 v[64:65], v[64:65], 0, v[136:137]
	global_store_dword v[64:65], v66, off
.LBB0_1151:
	s_or_b64 exec, exec, s[28:29]
	v_or_b32_e32 v140, 48, v142
	v_ashrrev_i32_e32 v141, 31, v140
	v_lshlrev_b64 v[146:147], 14, v[140:141]
	s_waitcnt lgkmcnt(0)
	v_lshl_add_u64 v[64:65], s[10:11], 0, v[146:147]
	v_lshl_add_u64 v[72:73], v[64:65], 0, v[144:145]
	s_add_u32 s30, s10, 0x240000
	s_addc_u32 s31, s11, 0
	global_load_dwordx4 v[236:239], v254, s[30:31]
	global_load_dwordx4 v[240:243], v254, s[30:31] offset:64
	global_load_dwordx4 v[244:247], v254, s[30:31] offset:512
	global_load_dwordx4 v[248:251], v254, s[30:31] offset:576
	s_waitcnt vmcnt(16)
	v_pk_add_f32 v[72:73], v[36:37], v[204:205]
	v_pk_add_f32 v[64:65], v[44:45], v[208:209]
	v_pk_add_f32 v[44:45], v[88:89], v[212:213]
	v_pk_add_f32 v[36:37], v[76:77], v[216:217]
	v_mul_f32_e32 v76, v73, v73
	v_mul_f32_e32 v77, v65, v65
	v_pk_add_f32 v[74:75], v[38:39], v[206:207]
	v_pk_add_f32 v[66:67], v[46:47], v[210:211]
	v_pk_add_f32 v[38:39], v[78:79], v[218:219]
	v_mul_f32_e32 v78, v45, v45
	v_fmac_f32_e32 v76, v72, v72
	v_fmac_f32_e32 v77, v64, v64
	v_pk_add_f32 v[46:47], v[90:91], v[214:215]
	v_mul_f32_e32 v79, v37, v37
	v_fmac_f32_e32 v78, v44, v44
	v_fmac_f32_e32 v76, v74, v74
	v_fmac_f32_e32 v77, v66, v66
	v_fmac_f32_e32 v79, v36, v36
	v_fmac_f32_e32 v78, v46, v46
	v_fmac_f32_e32 v76, v75, v75
	v_fmac_f32_e32 v77, v67, v67
	v_fmac_f32_e32 v79, v38, v38
	v_fmac_f32_e32 v78, v47, v47
	v_add_f32_e32 v76, v76, v77
	v_add_f32_e32 v76, v76, v78
	v_fmac_f32_e32 v79, v39, v39
	v_add_f32_e32 v88, v76, v79
	ds_bpermute_b32 v89, v153, v88
	v_lshl_add_u64 v[76:77], s[6:7], 0, v[146:147]
	v_lshl_add_u64 v[78:79], v[76:77], 0, v[144:145]
	global_store_dwordx4 v[78:79], v[72:75], off
	global_store_dwordx4 v[78:79], v[64:67], off offset:64
	global_store_dwordx4 v[78:79], v[44:47], off offset:512
	global_store_dwordx4 v[78:79], v[36:39], off offset:576
	s_waitcnt lgkmcnt(0)
	v_add_f32_e32 v76, v88, v89
	ds_bpermute_b32 v77, v152, v76
	s_and_saveexec_b64 s[28:29], vcc
	s_cbranch_execz .LBB0_1153
	s_load_dwordx2 s[30:31], s[2:3], 0x120
	s_waitcnt lgkmcnt(0)
	v_add_f32_e32 v78, v76, v77
	v_lshlrev_b64 v[76:77], 8, v[140:141]
	v_lshl_add_u64 v[76:77], s[30:31], 0, v[76:77]
	v_lshl_add_u64 v[76:77], s[26:27], 2, v[76:77]
	v_lshl_add_u64 v[76:77], v[76:77], 0, v[136:137]
	global_store_dword v[76:77], v78, off
;     ...
; #pragma unroll
;     for (int ai = 0; ai < 2; ++ai)
; #pragma unroll
;       for (int m = 0; m < 4; ++m) {
;         const int row = brow + ai * HALF + wr * 64 + m * 16 + fr;
;         float ssq = 0.f;
; #pragma unroll
;         for (int bj = 0; bj < 2; ++bj)
; #pragma unroll
;           for (int n = 0; n < 2; ++n) {
;             const int col = bcol + bj * HALF + wc * 32 + n * 16 + fq * 4;
;             f32x4 v = acc[ai][bj][m][n];
;             v += *(const f32x4*)(res + (long)row * D + col);
;             if (EPI == 7) *(f32x4*)(outf + (long)row * D + col) = v;
;             acc[ai][bj][m][n] = v;
;             ssq += v[0] * v[0] + v[1] * v[1] + v[2] * v[2] + v[3] * v[3];
;           }
;         ssq += bperm(ssq, lane ^ 16);
;         ssq += bperm(ssq, lane ^ 32);
;         if (fq == 0) p->sspart[(long)row * 64 + pn_ * 4 + wc] = ssq;
;         __builtin_amdgcn_sched_barrier(0);
.LBB0_1153:
	s_or_b64 exec, exec, s[28:29]
	v_add_u32_e32 v140, 0x80, v142
	v_ashrrev_i32_e32 v141, 31, v140
	v_lshlrev_b64 v[146:147], 14, v[140:141]
	s_waitcnt lgkmcnt(0)
	v_lshl_add_u64 v[76:77], s[10:11], 0, v[146:147]
	v_lshl_add_u64 v[88:89], v[76:77], 0, v[144:145]
	s_add_u32 s30, s10, 0x280000
	s_addc_u32 s31, s11, 0
	global_load_dwordx4 v[204:207], v254, s[30:31]
	global_load_dwordx4 v[208:211], v254, s[30:31] offset:64
	global_load_dwordx4 v[212:215], v254, s[30:31] offset:512
	global_load_dwordx4 v[216:219], v254, s[30:31] offset:576
	s_waitcnt vmcnt(16)
	v_pk_add_f32 v[88:89], v[52:53], v[220:221]
	v_pk_add_f32 v[76:77], v[60:61], v[224:225]
	v_pk_add_f32 v[60:61], v[104:105], v[228:229]
	v_pk_add_f32 v[52:53], v[96:97], v[232:233]
	v_mul_f32_e32 v96, v89, v89
	v_mul_f32_e32 v97, v77, v77
	v_pk_add_f32 v[90:91], v[54:55], v[222:223]
	v_pk_add_f32 v[78:79], v[62:63], v[226:227]
	v_pk_add_f32 v[54:55], v[98:99], v[234:235]
	v_mul_f32_e32 v98, v61, v61
	v_fmac_f32_e32 v96, v88, v88
	v_fmac_f32_e32 v97, v76, v76
	v_pk_add_f32 v[62:63], v[106:107], v[230:231]
	v_mul_f32_e32 v99, v53, v53
	v_fmac_f32_e32 v98, v60, v60
	v_fmac_f32_e32 v96, v90, v90
	v_fmac_f32_e32 v97, v78, v78
	v_fmac_f32_e32 v99, v52, v52
	v_fmac_f32_e32 v98, v62, v62
	v_fmac_f32_e32 v96, v91, v91
	v_fmac_f32_e32 v97, v79, v79
	v_fmac_f32_e32 v99, v54, v54
	v_fmac_f32_e32 v98, v63, v63
	v_add_f32_e32 v96, v96, v97
	v_add_f32_e32 v96, v96, v98
	v_fmac_f32_e32 v99, v55, v55
	v_add_f32_e32 v100, v96, v99
	ds_bpermute_b32 v101, v153, v100
	v_lshl_add_u64 v[96:97], s[6:7], 0, v[146:147]
	v_lshl_add_u64 v[98:99], v[96:97], 0, v[144:145]
	global_store_dwordx4 v[98:99], v[88:91], off
	global_store_dwordx4 v[98:99], v[76:79], off offset:64
	global_store_dwordx4 v[98:99], v[60:63], off offset:512
	global_store_dwordx4 v[98:99], v[52:55], off offset:576
	s_waitcnt lgkmcnt(0)
	v_add_f32_e32 v96, v100, v101
	ds_bpermute_b32 v97, v152, v96
	s_and_saveexec_b64 s[28:29], vcc
	s_cbranch_execz .LBB0_1155
	s_load_dwordx2 s[30:31], s[2:3], 0x120
	s_waitcnt lgkmcnt(0)
	v_add_f32_e32 v98, v96, v97
	v_lshlrev_b64 v[96:97], 8, v[140:141]
	v_lshl_add_u64 v[96:97], s[30:31], 0, v[96:97]
	v_lshl_add_u64 v[96:97], s[26:27], 2, v[96:97]
	v_lshl_add_u64 v[96:97], v[96:97], 0, v[136:137]
	global_store_dword v[96:97], v98, off
.LBB0_1155:
	s_or_b64 exec, exec, s[28:29]
	v_add_u32_e32 v140, 0x90, v142
	v_ashrrev_i32_e32 v141, 31, v140
	v_lshlrev_b64 v[146:147], 14, v[140:141]
	s_waitcnt lgkmcnt(0)
	v_lshl_add_u64 v[96:97], s[10:11], 0, v[146:147]
	v_lshl_add_u64 v[104:105], v[96:97], 0, v[144:145]
	s_add_u32 s30, s10, 0x2c0000
	s_addc_u32 s31, s11, 0
	global_load_dwordx4 v[220:223], v254, s[30:31]
	global_load_dwordx4 v[224:227], v254, s[30:31] offset:64
	global_load_dwordx4 v[228:231], v254, s[30:31] offset:512
	global_load_dwordx4 v[232:235], v254, s[30:31] offset:576
	s_waitcnt vmcnt(16)
	v_pk_add_f32 v[104:105], v[68:69], v[236:237]
	v_pk_add_f32 v[96:97], v[80:81], v[240:241]
	v_pk_add_f32 v[80:81], v[116:117], v[244:245]
	v_mul_f32_e32 v100, v105, v105
	v_mul_f32_e32 v101, v97, v97
	v_pk_add_f32 v[106:107], v[70:71], v[238:239]
	v_pk_add_f32 v[98:99], v[82:83], v[242:243]
	v_pk_add_f32 v[68:69], v[108:109], v[248:249]
	v_mul_f32_e32 v102, v81, v81
	v_fmac_f32_e32 v100, v104, v104
	v_fmac_f32_e32 v101, v96, v96
	v_pk_add_f32 v[82:83], v[118:119], v[246:247]
	v_mul_f32_e32 v103, v69, v69
	v_fmac_f32_e32 v102, v80, v80
	v_fmac_f32_e32 v100, v106, v106
	v_fmac_f32_e32 v101, v98, v98
	v_pk_add_f32 v[70:71], v[110:111], v[250:251]
	v_fmac_f32_e32 v103, v68, v68
	v_fmac_f32_e32 v102, v82, v82
	v_fmac_f32_e32 v100, v107, v107
	v_fmac_f32_e32 v101, v99, v99
	v_fmac_f32_e32 v103, v70, v70
	v_fmac_f32_e32 v102, v83, v83
	v_add_f32_e32 v100, v100, v101
	v_add_f32_e32 v100, v100, v102
	v_fmac_f32_e32 v103, v71, v71
	v_add_f32_e32 v102, v100, v103
	ds_bpermute_b32 v103, v153, v102
	v_lshl_add_u64 v[100:101], s[6:7], 0, v[146:147]
	v_lshl_add_u64 v[100:101], v[100:101], 0, v[144:145]
	global_store_dwordx4 v[100:101], v[104:107], off
	global_store_dwordx4 v[100:101], v[96:99], off offset:64
	global_store_dwordx4 v[100:101], v[80:83], off offset:512
	global_store_dwordx4 v[100:101], v[68:71], off offset:576
	s_waitcnt lgkmcnt(0)
	v_add_f32_e32 v108, v102, v103
	ds_bpermute_b32 v109, v152, v108
	s_and_saveexec_b64 s[28:29], vcc
	s_cbranch_execz .LBB0_1157
	s_load_dwordx2 s[30:31], s[2:3], 0x120
	v_lshlrev_b64 v[100:101], 8, v[140:141]
	s_waitcnt lgkmcnt(0)
	v_add_f32_e32 v102, v108, v109
	v_lshl_add_u64 v[100:101], s[30:31], 0, v[100:101]
	v_lshl_add_u64 v[100:101], s[26:27], 2, v[100:101]
	v_lshl_add_u64 v[100:101], v[100:101], 0, v[136:137]
	global_store_dword v[100:101], v102, off
;     ...
; #pragma unroll
;     for (int ai = 0; ai < 2; ++ai)
; #pragma unroll
;       for (int m = 0; m < 4; ++m) {
;         const int row = brow + ai * HALF + wr * 64 + m * 16 + fr;
;         float ssq = 0.f;
; #pragma unroll
;         for (int bj = 0; bj < 2; ++bj)
; #pragma unroll
;           for (int n = 0; n < 2; ++n) {
;             const int col = bcol + bj * HALF + wc * 32 + n * 16 + fq * 4;
;             f32x4 v = acc[ai][bj][m][n];
;             v += *(const f32x4*)(res + (long)row * D + col);
;             if (EPI == 7) *(f32x4*)(outf + (long)row * D + col) = v;
;             acc[ai][bj][m][n] = v;
;             ssq += v[0] * v[0] + v[1] * v[1] + v[2] * v[2] + v[3] * v[3];
;           }
;         ssq += bperm(ssq, lane ^ 16);
;         ssq += bperm(ssq, lane ^ 32);
;         if (fq == 0) p->sspart[(long)row * 64 + pn_ * 4 + wc] = ssq;
;         __builtin_amdgcn_sched_barrier(0);
.LBB0_1157:
	s_or_b64 exec, exec, s[28:29]
	v_add_u32_e32 v146, 0xa0, v142
	v_ashrrev_i32_e32 v147, 31, v146
	v_lshlrev_b64 v[162:163], 14, v[146:147]
	v_lshl_add_u64 v[100:101], s[10:11], 0, v[162:163]
	v_lshl_add_u64 v[116:117], v[100:101], 0, v[144:145]
	s_waitcnt lgkmcnt(0)
	s_waitcnt vmcnt(12)
	v_pk_add_f32 v[116:117], v[84:85], v[204:205]
	v_pk_add_f32 v[108:109], v[92:93], v[208:209]
	v_pk_add_f32 v[92:93], v[124:125], v[212:213]
	v_mul_f32_e32 v100, v117, v117
	v_mul_f32_e32 v101, v109, v109
	v_pk_add_f32 v[118:119], v[86:87], v[206:207]
	v_pk_add_f32 v[110:111], v[94:95], v[210:211]
	v_pk_add_f32 v[84:85], v[120:121], v[216:217]
	v_mul_f32_e32 v102, v93, v93
	v_fmac_f32_e32 v100, v116, v116
	v_fmac_f32_e32 v101, v108, v108
	v_pk_add_f32 v[94:95], v[126:127], v[214:215]
	v_mul_f32_e32 v103, v85, v85
	v_fmac_f32_e32 v102, v92, v92
	v_fmac_f32_e32 v100, v118, v118
	v_fmac_f32_e32 v101, v110, v110
	v_pk_add_f32 v[86:87], v[122:123], v[218:219]
	v_fmac_f32_e32 v103, v84, v84
	v_fmac_f32_e32 v102, v94, v94
	v_fmac_f32_e32 v100, v119, v119
	v_fmac_f32_e32 v101, v111, v111
	v_fmac_f32_e32 v103, v86, v86
	v_fmac_f32_e32 v102, v95, v95
	v_add_f32_e32 v100, v100, v101
	v_add_f32_e32 v100, v100, v102
	v_fmac_f32_e32 v103, v87, v87
	v_add_f32_e32 v102, v100, v103
	ds_bpermute_b32 v103, v153, v102
	v_lshl_add_u64 v[100:101], s[6:7], 0, v[162:163]
	v_lshl_add_u64 v[100:101], v[100:101], 0, v[144:145]
	global_store_dwordx4 v[100:101], v[116:119], off
	global_store_dwordx4 v[100:101], v[108:111], off offset:64
	global_store_dwordx4 v[100:101], v[92:95], off offset:512
	global_store_dwordx4 v[100:101], v[84:87], off offset:576
	s_waitcnt lgkmcnt(0)
	v_add_f32_e32 v120, v102, v103
	ds_bpermute_b32 v121, v152, v120
	s_and_saveexec_b64 s[28:29], vcc
	s_cbranch_execz .LBB0_1159
	s_load_dwordx2 s[30:31], s[2:3], 0x120
	v_lshlrev_b64 v[100:101], 8, v[146:147]
	s_waitcnt lgkmcnt(0)
	v_add_f32_e32 v102, v120, v121
	v_lshl_add_u64 v[100:101], s[30:31], 0, v[100:101]
	v_lshl_add_u64 v[100:101], s[26:27], 2, v[100:101]
	v_lshl_add_u64 v[100:101], v[100:101], 0, v[136:137]
	global_store_dword v[100:101], v102, off
.LBB0_1159:
	s_or_b64 exec, exec, s[28:29]
	v_add_u32_e32 v142, 0xb0, v142
	v_ashrrev_i32_e32 v143, 31, v142
	v_lshlrev_b64 v[146:147], 14, v[142:143]
	v_lshl_add_u64 v[100:101], s[10:11], 0, v[146:147]
	v_lshl_add_u64 v[124:125], v[100:101], 0, v[144:145]
	s_waitcnt lgkmcnt(0)
	s_waitcnt vmcnt(8)
	v_pk_add_f32 v[124:125], v[174:175], v[220:221]
	v_pk_add_f32 v[120:121], v[112:113], v[224:225]
	v_pk_add_f32 v[112:113], v[132:133], v[228:229]
	v_pk_add_f32 v[100:101], v[128:129], v[232:233]
	v_mul_f32_e32 v128, v125, v125
	v_mul_f32_e32 v129, v121, v121
	v_pk_add_f32 v[126:127], v[176:177], v[222:223]
	v_pk_add_f32 v[122:123], v[114:115], v[226:227]
	v_pk_add_f32 v[102:103], v[130:131], v[234:235]
	v_mul_f32_e32 v130, v113, v113
	v_fmac_f32_e32 v128, v124, v124
	v_fmac_f32_e32 v129, v120, v120
	v_pk_add_f32 v[114:115], v[134:135], v[230:231]
	v_mul_f32_e32 v131, v101, v101
	v_fmac_f32_e32 v130, v112, v112
	v_fmac_f32_e32 v128, v126, v126
	v_fmac_f32_e32 v129, v122, v122
	v_fmac_f32_e32 v131, v100, v100
	v_fmac_f32_e32 v130, v114, v114
	v_fmac_f32_e32 v128, v127, v127
	v_fmac_f32_e32 v129, v123, v123
	v_fmac_f32_e32 v131, v102, v102
	v_fmac_f32_e32 v130, v115, v115
	v_add_f32_e32 v128, v128, v129
	v_add_f32_e32 v128, v128, v130
	v_fmac_f32_e32 v131, v103, v103
	v_add_f32_e32 v132, v128, v131
	ds_bpermute_b32 v133, v153, v132
	v_lshl_add_u64 v[128:129], s[6:7], 0, v[146:147]
	v_lshl_add_u64 v[130:131], v[128:129], 0, v[144:145]
	global_store_dwordx4 v[130:131], v[124:127], off
	global_store_dwordx4 v[130:131], v[120:123], off offset:64
	global_store_dwordx4 v[130:131], v[112:115], off offset:512
	global_store_dwordx4 v[130:131], v[100:103], off offset:576
	s_waitcnt lgkmcnt(0)
	v_add_f32_e32 v128, v132, v133
	ds_bpermute_b32 v129, v152, v128
	s_and_saveexec_b64 s[28:29], vcc
	s_cbranch_execz .LBB0_1161
	s_load_dwordx2 s[30:31], s[2:3], 0x120
	s_waitcnt lgkmcnt(0)
	v_add_f32_e32 v130, v128, v129
	v_lshlrev_b64 v[128:129], 8, v[142:143]
	v_lshl_add_u64 v[128:129], s[30:31], 0, v[128:129]
	v_lshl_add_u64 v[128:129], s[26:27], 2, v[128:129]
	v_lshl_add_u64 v[128:129], v[128:129], 0, v[136:137]
	global_store_dword v[128:129], v130, off

;     ...
; #pragma unroll
;     for (int ai = 0; ai < 2; ++ai)
; #pragma unroll
;       for (int m = 0; m < 4; ++m) {
;         const int row = brow + ai * HALF + wr * 64 + m * 16 + fr;
;         float ssq = 0.f;
; #pragma unroll
;         for (int bj = 0; bj < 2; ++bj)
; #pragma unroll
;           for (int n = 0; n < 2; ++n) {
;             const int col = bcol + bj * HALF + wc * 32 + n * 16 + fq * 4;
;             f32x4 v = acc[ai][bj][m][n];
;             v += *(const f32x4*)(res + (long)row * D + col);
;             if (EPI == 7) *(f32x4*)(outf + (long)row * D + col) = v;
;             acc[ai][bj][m][n] = v;
;             ssq += v[0] * v[0] + v[1] * v[1] + v[2] * v[2] + v[3] * v[3];
;           }
;         ssq += bperm(ssq, lane ^ 16);
;         ssq += bperm(ssq, lane ^ 32);
;         if (fq == 0) p->sspart[(long)row * 64 + pn_ * 4 + wc] = ssq;
;         __builtin_amdgcn_sched_barrier(0);
.LBB0_1338:
	s_or_b64 exec, exec, s[4:5]
	v_or_b32_e32 v128, s34, v142
	v_add_u32_e32 v142, v143, v128
	v_lshrrev_b32_e32 v130, 2, v140
	v_lshlrev_b32_e32 v128, 5, v141
	v_and_b32_e32 v130, 12, v130
	v_ashrrev_i32_e32 v143, 31, v142
	v_or3_b32 v130, v128, v130, s25
	v_lshlrev_b64 v[132:133], 14, v[142:143]
	v_lshl_add_u64 v[132:133], s[8:9], 0, v[132:133]
	v_ashrrev_i32_e32 v131, 31, v130
	v_lshl_add_u64 v[136:137], v[130:131], 2, v[132:133]
	v_lshlrev_b32_e32 v250, 14, v142
	v_lshl_add_u32 v250, v130, 2, v250
	s_mov_b64 s[22:23], s[8:9]
	global_load_dwordx4 v[206:209], v250, s[22:23]
	global_load_dwordx4 v[210:213], v250, s[22:23] offset:64
	global_load_dwordx4 v[214:217], v250, s[22:23] offset:512
	global_load_dwordx4 v[218:221], v250, s[22:23] offset:576
	s_add_u32 s22, s8, 0x40000
	s_addc_u32 s23, s9, 0
	global_load_dwordx4 v[222:225], v250, s[22:23]
	global_load_dwordx4 v[226:229], v250, s[22:23] offset:64
	global_load_dwordx4 v[230:233], v250, s[22:23] offset:512
	global_load_dwordx4 v[234:237], v250, s[22:23] offset:576
	v_and_b32_e32 v128, 63, v140
	v_lshlrev_b32_e32 v140, 2, v128
	v_xor_b32_e32 v150, 64, v140
	v_xor_b32_e32 v151, 0x80, v140
	s_ashr_i32 s4, s24, 1
	s_and_b32 s4, s4, -4
	v_cmp_gt_u32_e32 vcc, 16, v128
	s_ashr_i32 s5, s4, 31
	v_lshlrev_b32_e32 v128, 2, v141
	s_waitcnt vmcnt(4)
	v_pk_add_f32 v[136:137], v[114:115], v[208:209]
	v_pk_add_f32 v[138:139], v[112:113], v[206:207]
	v_pk_add_f32 v[134:135], v[116:117], v[210:211]
	v_pk_add_f32 v[132:133], v[118:119], v[212:213]
	v_pk_add_f32 v[118:119], v[124:125], v[214:215]
	v_pk_add_f32 v[114:115], v[120:121], v[218:219]
	v_mul_f32_e32 v120, v139, v139
	v_mul_f32_e32 v121, v135, v135
	v_pk_add_f32 v[112:113], v[122:123], v[220:221]
	v_mul_f32_e32 v122, v119, v119
	v_fmac_f32_e32 v120, v138, v138
	v_fmac_f32_e32 v121, v134, v134
	v_pk_add_f32 v[116:117], v[126:127], v[216:217]
	v_mul_f32_e32 v123, v115, v115
	v_fmac_f32_e32 v122, v118, v118
	v_fmac_f32_e32 v120, v136, v136
	v_fmac_f32_e32 v121, v132, v132
	v_fmac_f32_e32 v123, v114, v114
	v_fmac_f32_e32 v122, v116, v116
	v_fmac_f32_e32 v120, v137, v137
	v_fmac_f32_e32 v121, v133, v133
	v_fmac_f32_e32 v123, v112, v112
	v_fmac_f32_e32 v122, v117, v117
	v_add_f32_e32 v120, v120, v121
	v_add_f32_e32 v120, v120, v122
	v_fmac_f32_e32 v123, v113, v113
	v_add_f32_e32 v120, v120, v123
	ds_bpermute_b32 v121, v150, v120
	s_waitcnt lgkmcnt(0)
	v_add_f32_e32 v120, v120, v121
	ds_bpermute_b32 v121, v151, v120
	s_and_saveexec_b64 s[6:7], vcc
	s_cbranch_execz .LBB0_1340
	s_load_dwordx2 s[22:23], s[42:43], 0x120
	s_waitcnt lgkmcnt(0)
	v_add_f32_e32 v122, v120, v121
	v_lshlrev_b64 v[120:121], 8, v[142:143]
	v_lshl_add_u64 v[120:121], s[22:23], 0, v[120:121]
	v_lshl_add_u64 v[120:121], s[4:5], 2, v[120:121]
	v_lshl_add_u64 v[120:121], v[120:121], 0, v[128:129]
	global_store_dword v[120:121], v122, off
.LBB0_1340:
	s_or_b64 exec, exec, s[6:7]
	v_or_b32_e32 v140, 16, v142
	v_ashrrev_i32_e32 v141, 31, v140
	s_waitcnt lgkmcnt(0)
	v_lshlrev_b64 v[120:121], 14, v[140:141]
	v_lshl_add_u64 v[120:121], s[8:9], 0, v[120:121]
	v_lshl_add_u64 v[124:125], v[130:131], 2, v[120:121]
	s_add_u32 s22, s8, 0x80000
	s_addc_u32 s23, s9, 0
	global_load_dwordx4 v[206:209], v250, s[22:23]
	global_load_dwordx4 v[210:213], v250, s[22:23] offset:64
	global_load_dwordx4 v[214:217], v250, s[22:23] offset:512
	global_load_dwordx4 v[218:221], v250, s[22:23] offset:576
	s_waitcnt vmcnt(4)
	v_pk_add_f32 v[124:125], v[98:99], v[224:225]
	v_pk_add_f32 v[126:127], v[96:97], v[222:223]
	v_pk_add_f32 v[122:123], v[100:101], v[226:227]
	v_pk_add_f32 v[120:121], v[102:103], v[228:229]
	v_pk_add_f32 v[102:103], v[108:109], v[230:231]
	v_pk_add_f32 v[98:99], v[104:105], v[234:235]
	v_mul_f32_e32 v104, v127, v127
	v_mul_f32_e32 v105, v123, v123
	v_pk_add_f32 v[96:97], v[106:107], v[236:237]
	v_mul_f32_e32 v106, v103, v103
	v_fmac_f32_e32 v104, v126, v126
	v_fmac_f32_e32 v105, v122, v122
	v_pk_add_f32 v[100:101], v[110:111], v[232:233]
	v_mul_f32_e32 v107, v99, v99
	v_fmac_f32_e32 v106, v102, v102
	v_fmac_f32_e32 v104, v124, v124
	v_fmac_f32_e32 v105, v120, v120
	v_fmac_f32_e32 v107, v98, v98
	v_fmac_f32_e32 v106, v100, v100
	v_fmac_f32_e32 v104, v125, v125
	v_fmac_f32_e32 v105, v121, v121
	v_fmac_f32_e32 v107, v96, v96
	v_fmac_f32_e32 v106, v101, v101
	v_add_f32_e32 v104, v104, v105
	v_add_f32_e32 v104, v104, v106
	v_fmac_f32_e32 v107, v97, v97
	v_add_f32_e32 v104, v104, v107
	ds_bpermute_b32 v105, v150, v104
	s_waitcnt lgkmcnt(0)
	v_add_f32_e32 v104, v104, v105
	ds_bpermute_b32 v105, v151, v104
	s_and_saveexec_b64 s[6:7], vcc
	s_cbranch_execz .LBB0_1342
	s_load_dwordx2 s[22:23], s[42:43], 0x120
	s_waitcnt lgkmcnt(0)
	v_add_f32_e32 v106, v104, v105
	v_lshlrev_b64 v[104:105], 8, v[140:141]
	v_lshl_add_u64 v[104:105], s[22:23], 0, v[104:105]
	v_lshl_add_u64 v[104:105], s[4:5], 2, v[104:105]
	v_lshl_add_u64 v[104:105], v[104:105], 0, v[128:129]
	global_store_dword v[104:105], v106, off
;     ...
; #pragma unroll
;     for (int ai = 0; ai < 2; ++ai)
; #pragma unroll
;       for (int m = 0; m < 4; ++m) {
;         const int row = brow + ai * HALF + wr * 64 + m * 16 + fr;
;         float ssq = 0.f;
; #pragma unroll
;         for (int bj = 0; bj < 2; ++bj)
; #pragma unroll
;           for (int n = 0; n < 2; ++n) {
;             const int col = bcol + bj * HALF + wc * 32 + n * 16 + fq * 4;
;             f32x4 v = acc[ai][bj][m][n];
;             v += *(const f32x4*)(res + (long)row * D + col);
;             if (EPI == 7) *(f32x4*)(outf + (long)row * D + col) = v;
;             acc[ai][bj][m][n] = v;
;             ssq += v[0] * v[0] + v[1] * v[1] + v[2] * v[2] + v[3] * v[3];
;           }
;         ssq += bperm(ssq, lane ^ 16);
;         ssq += bperm(ssq, lane ^ 32);
;         if (fq == 0) p->sspart[(long)row * 64 + pn_ * 4 + wc] = ssq;
;         __builtin_amdgcn_sched_barrier(0);
.LBB0_1342:
	s_or_b64 exec, exec, s[6:7]
	v_or_b32_e32 v140, 32, v142
	v_ashrrev_i32_e32 v141, 31, v140
	s_waitcnt lgkmcnt(0)
	v_lshlrev_b64 v[104:105], 14, v[140:141]
	v_lshl_add_u64 v[104:105], s[8:9], 0, v[104:105]
	v_lshl_add_u64 v[108:109], v[130:131], 2, v[104:105]
	s_add_u32 s22, s8, 0xc0000
	s_addc_u32 s23, s9, 0
	global_load_dwordx4 v[222:225], v250, s[22:23]
	global_load_dwordx4 v[226:229], v250, s[22:23] offset:64
	global_load_dwordx4 v[230:233], v250, s[22:23] offset:512
	global_load_dwordx4 v[234:237], v250, s[22:23] offset:576
	s_waitcnt vmcnt(4)
	v_pk_add_f32 v[108:109], v[82:83], v[208:209]
	v_pk_add_f32 v[110:111], v[80:81], v[206:207]
	v_pk_add_f32 v[106:107], v[84:85], v[210:211]
	v_pk_add_f32 v[104:105], v[86:87], v[212:213]
	v_pk_add_f32 v[86:87], v[92:93], v[214:215]
	v_pk_add_f32 v[82:83], v[88:89], v[218:219]
	v_mul_f32_e32 v88, v111, v111
	v_mul_f32_e32 v89, v107, v107
	v_pk_add_f32 v[80:81], v[90:91], v[220:221]
	v_mul_f32_e32 v90, v87, v87
	v_fmac_f32_e32 v88, v110, v110
	v_fmac_f32_e32 v89, v106, v106
	v_pk_add_f32 v[84:85], v[94:95], v[216:217]
	v_mul_f32_e32 v91, v83, v83
	v_fmac_f32_e32 v90, v86, v86
	v_fmac_f32_e32 v88, v108, v108
	v_fmac_f32_e32 v89, v104, v104
	v_fmac_f32_e32 v91, v82, v82
	v_fmac_f32_e32 v90, v84, v84
	v_fmac_f32_e32 v88, v109, v109
	v_fmac_f32_e32 v89, v105, v105
	v_fmac_f32_e32 v91, v80, v80
	v_fmac_f32_e32 v90, v85, v85
	v_add_f32_e32 v88, v88, v89
	v_add_f32_e32 v88, v88, v90
	v_fmac_f32_e32 v91, v81, v81
	v_add_f32_e32 v88, v88, v91
	ds_bpermute_b32 v89, v150, v88
	s_waitcnt lgkmcnt(0)
	v_add_f32_e32 v88, v88, v89
	ds_bpermute_b32 v89, v151, v88
	s_and_saveexec_b64 s[6:7], vcc
	s_cbranch_execz .LBB0_1344
	s_load_dwordx2 s[22:23], s[42:43], 0x120
	s_waitcnt lgkmcnt(0)
	v_add_f32_e32 v90, v88, v89
	v_lshlrev_b64 v[88:89], 8, v[140:141]
	v_lshl_add_u64 v[88:89], s[22:23], 0, v[88:89]
	v_lshl_add_u64 v[88:89], s[4:5], 2, v[88:89]
	v_lshl_add_u64 v[88:89], v[88:89], 0, v[128:129]
	global_store_dword v[88:89], v90, off
.LBB0_1344:
	s_or_b64 exec, exec, s[6:7]
	v_or_b32_e32 v140, 48, v142
	v_ashrrev_i32_e32 v141, 31, v140
	s_waitcnt lgkmcnt(0)
	v_lshlrev_b64 v[88:89], 14, v[140:141]
	v_lshl_add_u64 v[88:89], s[8:9], 0, v[88:89]
	v_lshl_add_u64 v[92:93], v[130:131], 2, v[88:89]
	s_add_u32 s22, s8, 0x200000
	s_addc_u32 s23, s9, 0
	global_load_dwordx4 v[206:209], v250, s[22:23]
	global_load_dwordx4 v[210:213], v250, s[22:23] offset:64
	global_load_dwordx4 v[214:217], v250, s[22:23] offset:512
	global_load_dwordx4 v[218:221], v250, s[22:23] offset:576
	s_waitcnt vmcnt(4)
	v_pk_add_f32 v[92:93], v[66:67], v[224:225]
	v_pk_add_f32 v[94:95], v[64:65], v[222:223]
	v_pk_add_f32 v[90:91], v[68:69], v[226:227]
	v_pk_add_f32 v[88:89], v[70:71], v[228:229]
	v_pk_add_f32 v[70:71], v[76:77], v[230:231]
	v_pk_add_f32 v[66:67], v[72:73], v[234:235]
	v_mul_f32_e32 v72, v95, v95
	v_mul_f32_e32 v73, v91, v91
	v_pk_add_f32 v[64:65], v[74:75], v[236:237]
	v_mul_f32_e32 v74, v71, v71
	v_fmac_f32_e32 v72, v94, v94
	v_fmac_f32_e32 v73, v90, v90
	v_pk_add_f32 v[68:69], v[78:79], v[232:233]
	v_mul_f32_e32 v75, v67, v67
	v_fmac_f32_e32 v74, v70, v70
	v_fmac_f32_e32 v72, v92, v92
	v_fmac_f32_e32 v73, v88, v88
	v_fmac_f32_e32 v75, v66, v66
	v_fmac_f32_e32 v74, v68, v68
	v_fmac_f32_e32 v72, v93, v93
	v_fmac_f32_e32 v73, v89, v89
	v_fmac_f32_e32 v75, v64, v64
	v_fmac_f32_e32 v74, v69, v69
	v_add_f32_e32 v72, v72, v73
	v_add_f32_e32 v72, v72, v74
	v_fmac_f32_e32 v75, v65, v65
	v_add_f32_e32 v72, v72, v75
	ds_bpermute_b32 v73, v150, v72
	s_waitcnt lgkmcnt(0)
	v_add_f32_e32 v72, v72, v73
	ds_bpermute_b32 v73, v151, v72
	s_and_saveexec_b64 s[6:7], vcc
	s_cbranch_execz .LBB0_1346
	s_load_dwordx2 s[22:23], s[42:43], 0x120
	s_waitcnt lgkmcnt(0)
	v_add_f32_e32 v74, v72, v73
	v_lshlrev_b64 v[72:73], 8, v[140:141]
	v_lshl_add_u64 v[72:73], s[22:23], 0, v[72:73]
	v_lshl_add_u64 v[72:73], s[4:5], 2, v[72:73]
	v_lshl_add_u64 v[72:73], v[72:73], 0, v[128:129]
	global_store_dword v[72:73], v74, off
.LBB0_1346:
	s_or_b64 exec, exec, s[6:7]
	v_add_u32_e32 v140, 0x80, v142
	v_ashrrev_i32_e32 v141, 31, v140
	s_waitcnt lgkmcnt(0)
	v_lshlrev_b64 v[72:73], 14, v[140:141]
	v_lshl_add_u64 v[72:73], s[8:9], 0, v[72:73]
	v_lshl_add_u64 v[76:77], v[130:131], 2, v[72:73]
	s_add_u32 s22, s8, 0x240000
	s_addc_u32 s23, s9, 0
	global_load_dwordx4 v[222:225], v250, s[22:23]
	global_load_dwordx4 v[226:229], v250, s[22:23] offset:64
	global_load_dwordx4 v[230:233], v250, s[22:23] offset:512
	global_load_dwordx4 v[234:237], v250, s[22:23] offset:576
	s_waitcnt vmcnt(4)
	v_pk_add_f32 v[76:77], v[50:51], v[208:209]
	v_pk_add_f32 v[78:79], v[48:49], v[206:207]
	v_pk_add_f32 v[74:75], v[52:53], v[210:211]
	v_pk_add_f32 v[72:73], v[54:55], v[212:213]
	v_pk_add_f32 v[54:55], v[60:61], v[214:215]
	v_pk_add_f32 v[50:51], v[56:57], v[218:219]
	v_mul_f32_e32 v56, v79, v79
	v_mul_f32_e32 v57, v75, v75
	v_pk_add_f32 v[48:49], v[58:59], v[220:221]
	v_mul_f32_e32 v58, v55, v55
	v_fmac_f32_e32 v56, v78, v78
	v_fmac_f32_e32 v57, v74, v74
	v_pk_add_f32 v[52:53], v[62:63], v[216:217]
	v_mul_f32_e32 v59, v51, v51
	v_fmac_f32_e32 v58, v54, v54
	v_fmac_f32_e32 v56, v76, v76
	v_fmac_f32_e32 v57, v72, v72
	v_fmac_f32_e32 v59, v50, v50
	v_fmac_f32_e32 v58, v52, v52
	v_fmac_f32_e32 v56, v77, v77
	v_fmac_f32_e32 v57, v73, v73
	v_fmac_f32_e32 v59, v48, v48
	v_fmac_f32_e32 v58, v53, v53
	v_add_f32_e32 v56, v56, v57
	v_add_f32_e32 v56, v56, v58
	v_fmac_f32_e32 v59, v49, v49
	v_add_f32_e32 v56, v56, v59
	ds_bpermute_b32 v57, v150, v56
	s_waitcnt lgkmcnt(0)
	v_add_f32_e32 v56, v56, v57
	ds_bpermute_b32 v57, v151, v56
	s_and_saveexec_b64 s[6:7], vcc
	s_cbranch_execz .LBB0_1348
	s_load_dwordx2 s[22:23], s[42:43], 0x120
	s_waitcnt lgkmcnt(0)
	v_add_f32_e32 v58, v56, v57
	v_lshlrev_b64 v[56:57], 8, v[140:141]
	v_lshl_add_u64 v[56:57], s[22:23], 0, v[56:57]
	v_lshl_add_u64 v[56:57], s[4:5], 2, v[56:57]
	v_lshl_add_u64 v[56:57], v[56:57], 0, v[128:129]
	global_store_dword v[56:57], v58, off
;     ...
; #pragma unroll
;     for (int ai = 0; ai < 2; ++ai)
; #pragma unroll
;       for (int m = 0; m < 4; ++m) {
;         const int row = brow + ai * HALF + wr * 64 + m * 16 + fr;
;         float ssq = 0.f;
; #pragma unroll
;         for (int bj = 0; bj < 2; ++bj)
; #pragma unroll
;           for (int n = 0; n < 2; ++n) {
;             const int col = bcol + bj * HALF + wc * 32 + n * 16 + fq * 4;
;             f32x4 v = acc[ai][bj][m][n];
;             v += *(const f32x4*)(res + (long)row * D + col);
;             if (EPI == 7) *(f32x4*)(outf + (long)row * D + col) = v;
;             acc[ai][bj][m][n] = v;
;             ssq += v[0] * v[0] + v[1] * v[1] + v[2] * v[2] + v[3] * v[3];
;           }
;         ssq += bperm(ssq, lane ^ 16);
;         ssq += bperm(ssq, lane ^ 32);
;         if (fq == 0) p->sspart[(long)row * 64 + pn_ * 4 + wc] = ssq;
;         __builtin_amdgcn_sched_barrier(0);
.LBB0_1348:
	s_or_b64 exec, exec, s[6:7]
	v_add_u32_e32 v144, 0x90, v142
	v_ashrrev_i32_e32 v145, 31, v144
	s_waitcnt lgkmcnt(0)
	v_lshlrev_b64 v[56:57], 14, v[144:145]
	v_lshl_add_u64 v[58:59], s[8:9], 0, v[56:57]
	v_lshl_add_u64 v[62:63], v[130:131], 2, v[58:59]
	s_add_u32 s22, s8, 0x280000
	s_addc_u32 s23, s9, 0
	global_load_dwordx4 v[206:209], v250, s[22:23]
	global_load_dwordx4 v[210:213], v250, s[22:23] offset:64
	global_load_dwordx4 v[214:217], v250, s[22:23] offset:512
	global_load_dwordx4 v[218:221], v250, s[22:23] offset:576
	s_waitcnt vmcnt(4)
	v_pk_add_f32 v[62:63], v[34:35], v[224:225]
	v_pk_add_f32 v[140:141], v[32:33], v[222:223]
	v_pk_add_f32 v[60:61], v[36:37], v[226:227]
	v_pk_add_f32 v[58:59], v[38:39], v[228:229]
	v_pk_add_f32 v[38:39], v[44:45], v[230:231]
	v_pk_add_f32 v[34:35], v[40:41], v[234:235]
	v_mul_f32_e32 v40, v141, v141
	v_mul_f32_e32 v41, v61, v61
	v_pk_add_f32 v[32:33], v[42:43], v[236:237]
	v_mul_f32_e32 v42, v39, v39
	v_fmac_f32_e32 v40, v140, v140
	v_fmac_f32_e32 v41, v60, v60
	v_pk_add_f32 v[36:37], v[46:47], v[232:233]
	v_mul_f32_e32 v43, v35, v35
	v_fmac_f32_e32 v42, v38, v38
	v_fmac_f32_e32 v40, v62, v62
	v_fmac_f32_e32 v41, v58, v58
	v_fmac_f32_e32 v43, v34, v34
	v_fmac_f32_e32 v42, v36, v36
	v_fmac_f32_e32 v40, v63, v63
	v_fmac_f32_e32 v41, v59, v59
	v_fmac_f32_e32 v43, v32, v32
	v_fmac_f32_e32 v42, v37, v37
	v_add_f32_e32 v40, v40, v41
	v_add_f32_e32 v40, v40, v42
	v_fmac_f32_e32 v43, v33, v33
	v_add_f32_e32 v40, v40, v43
	ds_bpermute_b32 v41, v150, v40
	s_waitcnt lgkmcnt(0)
	v_add_f32_e32 v40, v40, v41
	ds_bpermute_b32 v41, v151, v40
	s_and_saveexec_b64 s[6:7], vcc
	s_cbranch_execz .LBB0_1350
	s_load_dwordx2 s[22:23], s[42:43], 0x120
	s_waitcnt lgkmcnt(0)
	v_add_f32_e32 v42, v40, v41
	v_lshlrev_b64 v[40:41], 8, v[144:145]
	v_lshl_add_u64 v[40:41], s[22:23], 0, v[40:41]
	v_lshl_add_u64 v[40:41], s[4:5], 2, v[40:41]
	v_lshl_add_u64 v[40:41], v[40:41], 0, v[128:129]
	global_store_dword v[40:41], v42, off
.LBB0_1350:
	s_or_b64 exec, exec, s[6:7]
	v_add_u32_e32 v144, 0xa0, v142
	v_ashrrev_i32_e32 v145, 31, v144
	s_waitcnt lgkmcnt(0)
	v_lshlrev_b64 v[40:41], 14, v[144:145]
	v_lshl_add_u64 v[40:41], s[8:9], 0, v[40:41]
	v_lshl_add_u64 v[44:45], v[130:131], 2, v[40:41]
	s_add_u32 s22, s8, 0x2c0000
	s_addc_u32 s23, s9, 0
	global_load_dwordx4 v[222:225], v250, s[22:23]
	global_load_dwordx4 v[226:229], v250, s[22:23] offset:64
	global_load_dwordx4 v[230:233], v250, s[22:23] offset:512
	global_load_dwordx4 v[234:237], v250, s[22:23] offset:576
	s_waitcnt vmcnt(4)
	v_pk_add_f32 v[44:45], v[18:19], v[208:209]
	v_pk_add_f32 v[46:47], v[16:17], v[206:207]
	v_pk_add_f32 v[42:43], v[20:21], v[210:211]
	v_pk_add_f32 v[40:41], v[22:23], v[212:213]
	v_pk_add_f32 v[22:23], v[28:29], v[214:215]
	v_pk_add_f32 v[18:19], v[24:25], v[218:219]
	v_mul_f32_e32 v24, v47, v47
	v_mul_f32_e32 v25, v43, v43
	v_pk_add_f32 v[16:17], v[26:27], v[220:221]
	v_mul_f32_e32 v26, v23, v23
	v_fmac_f32_e32 v24, v46, v46
	v_fmac_f32_e32 v25, v42, v42
	v_pk_add_f32 v[20:21], v[30:31], v[216:217]
	v_mul_f32_e32 v27, v19, v19
	v_fmac_f32_e32 v26, v22, v22
	v_fmac_f32_e32 v24, v44, v44
	v_fmac_f32_e32 v25, v40, v40
	v_fmac_f32_e32 v27, v18, v18
	v_fmac_f32_e32 v26, v20, v20
	v_fmac_f32_e32 v24, v45, v45
	v_fmac_f32_e32 v25, v41, v41
	v_fmac_f32_e32 v27, v16, v16
	v_fmac_f32_e32 v26, v21, v21
	v_add_f32_e32 v24, v24, v25
	v_add_f32_e32 v24, v24, v26
	v_fmac_f32_e32 v27, v17, v17
	v_add_f32_e32 v24, v24, v27
	ds_bpermute_b32 v25, v150, v24
	s_waitcnt lgkmcnt(0)
	v_add_f32_e32 v24, v24, v25
	ds_bpermute_b32 v25, v151, v24
	s_and_saveexec_b64 s[6:7], vcc
	s_cbranch_execz .LBB0_1352
	s_load_dwordx2 s[22:23], s[42:43], 0x120
	s_waitcnt lgkmcnt(0)
	v_add_f32_e32 v26, v24, v25
	v_lshlrev_b64 v[24:25], 8, v[144:145]
	v_lshl_add_u64 v[24:25], s[22:23], 0, v[24:25]
	v_lshl_add_u64 v[24:25], s[4:5], 2, v[24:25]
	v_lshl_add_u64 v[24:25], v[24:25], 0, v[128:129]
	global_store_dword v[24:25], v26, off
.LBB0_1352:
	s_or_b64 exec, exec, s[6:7]
	v_add_u32_e32 v144, 0xb0, v142
	v_ashrrev_i32_e32 v145, 31, v144
	s_waitcnt lgkmcnt(0)
	v_lshlrev_b64 v[24:25], 14, v[144:145]
	v_lshl_add_u64 v[26:27], s[8:9], 0, v[24:25]
	v_lshl_add_u64 v[30:31], v[130:131], 2, v[26:27]
	s_waitcnt vmcnt(0)
	v_pk_add_f32 v[30:31], v[2:3], v[224:225]
	v_pk_add_f32 v[142:143], v[0:1], v[222:223]
	v_pk_add_f32 v[28:29], v[4:5], v[226:227]
	v_pk_add_f32 v[26:27], v[6:7], v[228:229]
	v_pk_add_f32 v[6:7], v[12:13], v[230:231]
	v_pk_add_f32 v[2:3], v[8:9], v[234:235]
	v_mul_f32_e32 v8, v143, v143
	v_mul_f32_e32 v9, v29, v29
	v_pk_add_f32 v[0:1], v[10:11], v[236:237]
	v_mul_f32_e32 v10, v7, v7
	v_fmac_f32_e32 v8, v142, v142
	v_fmac_f32_e32 v9, v28, v28
	v_pk_add_f32 v[4:5], v[14:15], v[232:233]
	v_mul_f32_e32 v11, v3, v3
	v_fmac_f32_e32 v10, v6, v6
	v_fmac_f32_e32 v8, v30, v30
	v_fmac_f32_e32 v9, v26, v26
	v_fmac_f32_e32 v11, v2, v2
	v_fmac_f32_e32 v10, v4, v4
	v_fmac_f32_e32 v8, v31, v31
	v_fmac_f32_e32 v9, v27, v27
	v_fmac_f32_e32 v11, v0, v0
	v_fmac_f32_e32 v10, v5, v5
	v_add_f32_e32 v8, v8, v9
	v_add_f32_e32 v8, v8, v10
	v_fmac_f32_e32 v11, v1, v1
	v_add_f32_e32 v8, v8, v11
	ds_bpermute_b32 v9, v150, v8
	s_waitcnt lgkmcnt(0)
	v_add_f32_e32 v8, v8, v9
	ds_bpermute_b32 v9, v151, v8
	s_and_saveexec_b64 s[6:7], vcc
	s_cbranch_execz .LBB0_1354
	s_load_dwordx2 s[22:23], s[42:43], 0x120
	s_waitcnt lgkmcnt(0)
	v_add_f32_e32 v10, v8, v9
	v_lshlrev_b64 v[8:9], 8, v[144:145]
	v_lshl_add_u64 v[8:9], s[22:23], 0, v[8:9]
	v_lshl_add_u64 v[8:9], s[4:5], 2, v[8:9]
	v_lshl_add_u64 v[8:9], v[8:9], 0, v[128:129]
	global_store_dword v[8:9], v10, off
